# gla chains start about 1 us late (2 x s_sleep 20) on top of the paced gla loader, leaving the gdn chains' first requests alone
# baseline (speedup 1.0000x reference)
; #define LBAR() do { asm volatile("s_waitcnt lgkmcnt(0)" ::: "memory"); __builtin_amdgcn_s_barrier(); asm volatile("" ::: "memory"); } while (0)
; #define WAITV(N_) asm volatile("s_waitcnt vmcnt(" #N_ ")" ::: "memory")
; #define ISSUE_XG(s_) do { const unsigned char* g_ = A.blob + (unit0 + CHUNK_OF(s_)) * BLOB + lane * 16; const unsigned l_ = lds0 + ((s_) & 1) * C_BUF; \
;         _Pragma("unroll") for (int k = 0; k < 8; ++k) { const unsigned o_ = (lw + 4 * k) * 1024; DMA1(g_ + o_, l_ + o_); __builtin_amdgcn_s_sleep(LOADER_PACE); } } while (0)
; #define WAITV(N_) asm volatile("s_waitcnt vmcnt(" #N_ ")" ::: "memory")
; __device__ __forceinline__ void gla_chain_unit(LAS unsigned char* lds, const GlaChainArgs& A, int item, int half) {
;     using namespace gla;
;     int tid_l = threadIdx.x; asm volatile("" : "+v"(tid_l));
;     const int tid = tid_l, lane = tid & 63, w = __builtin_amdgcn_readfirstlane(tid >> 6);
;     const int hh = lane >> 5;
;     const int c = item & 1, h = (item >> 1) & 3, sq = item >> 3;
;     ...
;     const int flags = A.flags;
;     ...
;     constexpr int flags = 0;
;     ...
;     const int ct = 4 * half + (w & 3), lw = w & 3;
;     const size_t unit0 = (size_t)(sq * 4 + h) * NCH;
;     const unsigned lds0 = (unsigned)(size_t)lds;
;     const bool probe = flags != 0;
;     ...
;     if (w >= 4) {
;         const unsigned qo = c ? B_QGB : B_QGF, ko = c ? B_KDTB : B_KDTF;
;     ...
;         if (!(flags & 4)) { ISSUE_XG(0); ISSUE_YG(0); ISSUE_XG(1); }
;         WAITV(0);
;         LBAR();
;         for (int s = 0; s < NCH; ++s) {
;             if (s + 1 < NCH && !(flags & 4)) ISSUE_YG(s + 1);
;             if (s <= NCH - 2 && !probe) WAITV(12); else WAITV(0);
;             LBAR();
;             if (s + 2 < NCH && !(flags & 4)) ISSUE_XG(s + 2);
;             if (s <= NCH - 3 && !probe) WAITV(12); else WAITV(0);
;             LBAR();
;         }
;     ...
;         return;
;     }
;     __builtin_amdgcn_s_setprio(2);
;     f32x16 S[4];
; #pragma unroll
;     for (int t = 0; t < 4; ++t) S[t] = zero16();
;     unsigned long long pwn[8] = {0ull, 0ull, 0ull, 0ull, 0ull, 0ull, 0ull, 0ull}; bool have = false; unsigned fnext = 0u;
;     LBAR();
.LBB0_589:
	s_and_b64 vcc, exec, s[2:3]
	s_cbranch_vccz .LBB0_625
	s_waitcnt vmcnt(0)
	s_sleep 20
	s_sleep 20
	v_mov_b32_e32 v3, v0
	s_nop 0
	v_readfirstlane_b32 s2, v3
	s_ashr_i32 s4, s2, 6
	v_and_b32_e32 v2, 63, v3
	s_and_b32 s46, s4, 3
	s_mov_b64 s[2:3], -1
	s_cmp_lt_i32 s4, 4
	v_lshlrev_b32_e32 v130, 4, v2
	s_cbranch_scc0 .LBB0_618
	v_readlane_b32 s2, v253, 34
	s_or_b32 s6, s46, s2
	s_setprio 2
	s_lshl_b32 s47, s46, 12
	s_lshl_b32 s4, s6, 12
	v_readlane_b32 s36, v251, 51
	v_lshrrev_b32_e32 v3, 3, v3
	v_readlane_b32 s37, v251, 52
	s_add_u32 s4, s36, s4
	v_and_b32_e32 v173, 4, v3
	v_cmp_eq_u32_e64 s[2:3], 0, v2
	s_addc_u32 s5, s37, 0
	v_lshlrev_b32_e32 v2, 3, v2
	v_mov_b32_e32 v3, v131
	s_waitcnt lgkmcnt(0)
	s_barrier
	v_lshl_add_u64 v[122:123], s[4:5], 0, v[2:3]
	s_lshl_b32 s4, s6, 2
	v_mov_b32_e32 v174, 0
	s_add_u32 s48, s91, s4
	s_addc_u32 s49, s90, 0
	s_mov_b64 s[36:37], -1
	s_mov_b64 s[6:7], 0
	v_mov_b64_e32 v[124:125], 0
	s_mov_b32 s50, 0
	v_mov_b64_e32 v[126:127], 0
	v_mov_b64_e32 v[128:129], 0
	v_mov_b64_e32 v[136:137], 0
	v_mov_b64_e32 v[138:139], 0
	v_mov_b64_e32 v[140:141], 0
	v_mov_b64_e32 v[142:143], 0
	v_mov_b64_e32 v[144:145], 0
	v_mov_b32_e32 v2, 0
	v_mov_b32_e32 v3, v174
	v_mov_b32_e32 v4, v174
	v_mov_b32_e32 v5, v174
	v_mov_b32_e32 v6, v174
	v_mov_b32_e32 v7, v174
	v_mov_b32_e32 v8, v174
	v_mov_b32_e32 v9, v174
	v_mov_b32_e32 v10, v174
	v_mov_b32_e32 v11, v174
	v_mov_b32_e32 v12, v174
	v_mov_b32_e32 v13, v174
	v_mov_b32_e32 v14, v174
	v_mov_b32_e32 v15, v174
	v_mov_b32_e32 v16, v174
	v_mov_b32_e32 v17, v174
	v_mov_b32_e32 v18, 0
	v_mov_b32_e32 v19, v174
	v_mov_b32_e32 v20, v174
	v_mov_b32_e32 v21, v174
	v_mov_b32_e32 v22, v174
	v_mov_b32_e32 v23, v174
	v_mov_b32_e32 v24, v174
	v_mov_b32_e32 v25, v174
	v_mov_b32_e32 v26, v174
	v_mov_b32_e32 v27, v174
	v_mov_b32_e32 v28, v174
	v_mov_b32_e32 v29, v174
	v_mov_b32_e32 v30, v174
	v_mov_b32_e32 v31, v174
	v_mov_b32_e32 v32, v174
	v_mov_b32_e32 v33, v174
	v_mov_b32_e32 v34, 0
	v_mov_b32_e32 v35, v174
	v_mov_b32_e32 v36, v174
	v_mov_b32_e32 v37, v174
	v_mov_b32_e32 v38, v174
	v_mov_b32_e32 v39, v174
	v_mov_b32_e32 v40, v174
	v_mov_b32_e32 v41, v174
	v_mov_b32_e32 v42, v174
	v_mov_b32_e32 v43, v174
	v_mov_b32_e32 v44, v174
	v_mov_b32_e32 v45, v174
	v_mov_b32_e32 v46, v174
	v_mov_b32_e32 v47, v174
	v_mov_b32_e32 v48, v174
	v_mov_b32_e32 v49, v174
	v_mov_b32_e32 v50, 0
	v_mov_b32_e32 v51, v174
	v_mov_b32_e32 v52, v174
	v_mov_b32_e32 v53, v174
	v_mov_b32_e32 v54, v174
	v_mov_b32_e32 v55, v174
	v_mov_b32_e32 v56, v174
	v_mov_b32_e32 v57, v174
	v_mov_b32_e32 v58, v174
	v_mov_b32_e32 v59, v174
	v_mov_b32_e32 v60, v174
	v_mov_b32_e32 v61, v174
	v_mov_b32_e32 v62, v174
	v_mov_b32_e32 v63, v174
	v_mov_b32_e32 v64, v174
	v_mov_b32_e32 v65, v174
	s_branch .LBB0_593
